# GEMM main loop: LDS-DMA global loads issued before the ds_reads in each of the four load segments (same instructions and waits)
# speedup vs baseline: 1.0047x; 1.0047x over previous
; #define PG8_STAGE(bufoff, gbase, voff) do { _Pragma("unroll") for (int _i = 0; _i < 2; ++_i) \
;         __builtin_amdgcn_global_load_lds((const unsigned*)((const char*)(gbase) + (voff)[_i]), (LAS unsigned*)(lds + (bufoff) + ldsw + _i * 8192), 16, 0, 0); } while (0)
; #define PG8_LDA(dst, b, h) do { _Pragma("unroll") for (int m = 0; m < 4; ++m) _Pragma("unroll") for (int k = 0; k < 2; ++k) dst[m][k] = *(const LAS bf16x8*)(lds + PG8_SA(b, h) + aoff + m * 2048 + k * 1024); } while (0)
; #define PG8_LDB(dst, b, h) do { _Pragma("unroll") for (int n = 0; n < 2; ++n) _Pragma("unroll") for (int k = 0; k < 2; ++k) dst[n][k] = *(const LAS bf16x8*)(lds + PG8_SB(b, h) + boff + n * 2048 + k * 1024); } while (0)
; #define PG8_MMA(ai, bj, At, Bt) do { __builtin_amdgcn_s_setprio(1); _Pragma("unroll") for (int m = 0; m < 4; ++m) _Pragma("unroll") for (int n = 0; n < 2; ++n) _Pragma("unroll") for (int k = 0; k < 2; ++k) \
;         acc[ai][bj][m][n] = __builtin_amdgcn_mfma_f32_16x16x32_bf16(Bt[n][k], At[m][k], acc[ai][bj][m][n], 0, 0, 0); __builtin_amdgcn_s_setprio(0); } while (0)
; #define PG8_WAIT_V(n) asm volatile("s_waitcnt vmcnt(" #n ")" ::: "memory")
; #define PG8_WAIT_L(n) asm volatile("s_waitcnt lgkmcnt(" #n ")" ::: "memory")
; #define PG8_BAR __builtin_amdgcn_s_barrier()
; #define PG8_SCHED __builtin_amdgcn_sched_barrier(0)
; template <class EpiT>
; __device__ __forceinline__ void gemm_phase(LAS unsigned char* lds, const Gemm g, const StaticOrder& S, const EpiT& E, int wv) {
;     ...
;             PG8_LDB(B0, 0, 0); PG8_LDB(B1, 0, 1); PG8_SCHED; PG8_LDA(At, 0, 0); PG8_STAGE(PG8_SA(1, 1), a1 + hA, voffA);
;             PG8_WAIT_V(8); PG8_WAIT_L(0); PG8_BAR; PG8_MMA(0, 0, At, B0); PG8_MMA(0, 1, At, B1); PG8_BAR; PG8_SCHED;
;             PG8_LDA(At, 0, 1); PG8_STAGE(PG8_SB(0, 0), b2, voffB); PG8_STAGE(PG8_SB(0, 1), b2 + hB, voffB); PG8_STAGE(PG8_SA(0, 0), a2, voffA);
;             PG8_WAIT_V(8); PG8_WAIT_L(0); PG8_BAR; PG8_MMA(1, 0, At, B0); PG8_MMA(1, 1, At, B1); PG8_BAR; PG8_SCHED;
.LBB0_271:
	s_add_i32 s42, s22, 2
	s_add_u32 s43, s0, 0x80
	s_addc_u32 s23, s1, 0
	s_add_i32 s64, 0, 0x10000
	s_cmp_eq_u32 s52, s22
	s_cselect_b32 s23, s19, s23
	s_cselect_b32 s22, s18, s43
	s_cselect_b32 s45, s21, s41
	s_cselect_b32 s44, s20, s40
	s_add_i32 s43, 0, 0x14000
	s_add_i32 m0, s14, 0xc000
	s_nop 0
	global_load_lds_dwordx4 v196, s[0:1]
	s_add_i32 m0, s14, 0xe000
	s_nop 0
	global_load_lds_dwordx4 v198, s[0:1]
	v_add_u32_e32 v0, s64, v234
	ds_read_b128 v[134:137], v0
	ds_read_b128 v[138:141], v0 offset:1024
	ds_read_b128 v[142:145], v0 offset:2048
	ds_read_b128 v[146:149], v0 offset:3072
	v_add_u32_e32 v0, s43, v234
	ds_read_b128 v[150:153], v0
	ds_read_b128 v[154:157], v0 offset:1024
	ds_read_b128 v[158:161], v0 offset:2048
	ds_read_b128 v[162:165], v0 offset:3072
	ds_read_b128 v[166:169], v242
	ds_read_b128 v[170:173], v242 offset:1024
	ds_read_b128 v[174:177], v242 offset:2048
	ds_read_b128 v[178:181], v242 offset:3072
	ds_read_b128 v[204:207], v242 offset:4096
	ds_read_b128 v[208:211], v242 offset:5120
	ds_read_b128 v[212:215], v242 offset:6144
	ds_read_b128 v[216:219], v242 offset:7168
	s_waitcnt vmcnt(8)
	s_waitcnt lgkmcnt(0)
	s_barrier
	s_setprio 1
	s_waitcnt lgkmcnt(0)
	v_mfma_f32_16x16x32_bf16 v[130:133], v[134:137], v[166:169], v[130:133]
	v_mfma_f32_16x16x32_bf16 v[126:129], v[142:145], v[166:169], v[126:129]
	v_mfma_f32_16x16x32_bf16 v[114:117], v[134:137], v[174:177], v[114:117]
	v_mfma_f32_16x16x32_bf16 v[110:113], v[142:145], v[174:177], v[110:113]
	v_mfma_f32_16x16x32_bf16 v[98:101], v[134:137], v[204:207], v[98:101]
	v_mfma_f32_16x16x32_bf16 v[94:97], v[142:145], v[204:207], v[94:97]
	v_mfma_f32_16x16x32_bf16 v[82:85], v[134:137], v[212:215], v[82:85]
	v_mfma_f32_16x16x32_bf16 v[78:81], v[142:145], v[212:215], v[78:81]
	v_mfma_f32_16x16x32_bf16 v[130:133], v[138:141], v[170:173], v[130:133]
	v_mfma_f32_16x16x32_bf16 v[126:129], v[146:149], v[170:173], v[126:129]
	v_mfma_f32_16x16x32_bf16 v[114:117], v[138:141], v[178:181], v[114:117]
	v_mfma_f32_16x16x32_bf16 v[110:113], v[146:149], v[178:181], v[110:113]
	v_mfma_f32_16x16x32_bf16 v[98:101], v[138:141], v[208:211], v[98:101]
	v_mfma_f32_16x16x32_bf16 v[94:97], v[146:149], v[208:211], v[94:97]
	v_mfma_f32_16x16x32_bf16 v[82:85], v[138:141], v[216:219], v[82:85]
	v_mfma_f32_16x16x32_bf16 v[78:81], v[146:149], v[216:219], v[78:81]
	s_setprio 0
	s_setprio 1
	v_mfma_f32_16x16x32_bf16 v[122:125], v[150:153], v[166:169], v[122:125]
	v_mfma_f32_16x16x32_bf16 v[118:121], v[158:161], v[166:169], v[118:121]
	v_mfma_f32_16x16x32_bf16 v[106:109], v[150:153], v[174:177], v[106:109]
	v_mfma_f32_16x16x32_bf16 v[102:105], v[158:161], v[174:177], v[102:105]
	v_mfma_f32_16x16x32_bf16 v[90:93], v[150:153], v[204:207], v[90:93]
	v_mfma_f32_16x16x32_bf16 v[86:89], v[158:161], v[204:207], v[86:89]
	v_mfma_f32_16x16x32_bf16 v[74:77], v[150:153], v[212:215], v[74:77]
	v_mfma_f32_16x16x32_bf16 v[70:73], v[158:161], v[212:215], v[70:73]
	v_mfma_f32_16x16x32_bf16 v[122:125], v[154:157], v[170:173], v[122:125]
	v_mfma_f32_16x16x32_bf16 v[118:121], v[162:165], v[170:173], v[118:121]
	v_mfma_f32_16x16x32_bf16 v[106:109], v[154:157], v[178:181], v[106:109]
	v_mfma_f32_16x16x32_bf16 v[102:105], v[162:165], v[178:181], v[102:105]
	v_mfma_f32_16x16x32_bf16 v[90:93], v[154:157], v[208:211], v[90:93]
	v_mfma_f32_16x16x32_bf16 v[86:89], v[162:165], v[208:211], v[86:89]
	v_mfma_f32_16x16x32_bf16 v[74:77], v[154:157], v[216:219], v[74:77]
	v_mfma_f32_16x16x32_bf16 v[70:73], v[162:165], v[216:219], v[70:73]
	s_setprio 0
	s_barrier
	s_add_i32 s64, s64, s13
	s_mov_b32 m0, s64
	s_add_u32 s36, s44, 0x80
	s_addc_u32 s37, s45, 0
	global_load_lds_dwordx4 v182, s[44:45]
	s_add_i32 m0, s64, 0x2000
	s_add_i32 s43, s43, s13
	global_load_lds_dwordx4 v186, s[44:45]
	s_add_u32 s44, s44, s8
	s_addc_u32 s45, s45, 0
	s_mov_b32 m0, s43
	s_add_u32 s38, s44, 0x80
	s_addc_u32 s39, s45, 0
	global_load_lds_dwordx4 v182, s[44:45]
	s_add_i32 m0, s43, 0x2000
	s_add_u32 s46, s22, 0x80
	s_addc_u32 s47, s23, 0
	global_load_lds_dwordx4 v186, s[44:45]
	s_mov_b32 m0, s14
	s_nop 0
	global_load_lds_dwordx4 v14, s[22:23]
	s_mov_b32 m0, s15
	s_nop 0
	global_load_lds_dwordx4 v184, s[22:23]
	ds_read_b128 v[166:169], v242 offset:16384
	ds_read_b128 v[170:173], v242 offset:17408
	ds_read_b128 v[174:177], v242 offset:18432
	ds_read_b128 v[178:181], v242 offset:19456
	ds_read_b128 v[204:207], v242 offset:20480
	ds_read_b128 v[208:211], v242 offset:21504
	ds_read_b128 v[212:215], v242 offset:22528
	ds_read_b128 v[216:219], v242 offset:23552
	s_waitcnt vmcnt(8)
	s_waitcnt lgkmcnt(0)
	s_barrier
; #define PG8_STAGE(bufoff, gbase, voff) do { _Pragma("unroll") for (int _i = 0; _i < 2; ++_i) \
;         __builtin_amdgcn_global_load_lds((const unsigned*)((const char*)(gbase) + (voff)[_i]), (LAS unsigned*)(lds + (bufoff) + ldsw + _i * 8192), 16, 0, 0); } while (0)
; #define PG8_LDA(dst, b, h) do { _Pragma("unroll") for (int m = 0; m < 4; ++m) _Pragma("unroll") for (int k = 0; k < 2; ++k) dst[m][k] = *(const LAS bf16x8*)(lds + PG8_SA(b, h) + aoff + m * 2048 + k * 1024); } while (0)
; #define PG8_LDB(dst, b, h) do { _Pragma("unroll") for (int n = 0; n < 2; ++n) _Pragma("unroll") for (int k = 0; k < 2; ++k) dst[n][k] = *(const LAS bf16x8*)(lds + PG8_SB(b, h) + boff + n * 2048 + k * 1024); } while (0)
; #define PG8_MMA(ai, bj, At, Bt) do { __builtin_amdgcn_s_setprio(1); _Pragma("unroll") for (int m = 0; m < 4; ++m) _Pragma("unroll") for (int n = 0; n < 2; ++n) _Pragma("unroll") for (int k = 0; k < 2; ++k) \
;         acc[ai][bj][m][n] = __builtin_amdgcn_mfma_f32_16x16x32_bf16(Bt[n][k], At[m][k], acc[ai][bj][m][n], 0, 0, 0); __builtin_amdgcn_s_setprio(0); } while (0)
; #define PG8_WAIT_V(n) asm volatile("s_waitcnt vmcnt(" #n ")" ::: "memory")
; #define PG8_WAIT_L(n) asm volatile("s_waitcnt lgkmcnt(" #n ")" ::: "memory")
; #define PG8_BAR __builtin_amdgcn_s_barrier()
; #define PG8_SCHED __builtin_amdgcn_sched_barrier(0)
; template <class EpiT>
; __device__ __forceinline__ void gemm_phase(LAS unsigned char* lds, const Gemm g, const StaticOrder& S, const EpiT& E, int wv) {
;     ...
;             PG8_WAIT_V(8); PG8_WAIT_L(0); PG8_BAR; PG8_MMA(1, 0, At, B0); PG8_MMA(1, 1, At, B1); PG8_BAR; PG8_SCHED;
;             PG8_LDB(B0, 1, 0); PG8_LDB(B1, 1, 1); PG8_SCHED; PG8_LDA(At, 1, 0); PG8_STAGE(PG8_SA(0, 1), a2 + hA, voffA);
;             PG8_WAIT_V(8); PG8_WAIT_L(0); PG8_BAR; PG8_MMA(0, 0, At, B0); PG8_MMA(0, 1, At, B1); PG8_BAR; PG8_SCHED;
	s_setprio 1
	s_waitcnt lgkmcnt(0)
	v_mfma_f32_16x16x32_bf16 v[66:69], v[134:137], v[166:169], v[66:69]
	v_mfma_f32_16x16x32_bf16 v[62:65], v[142:145], v[166:169], v[62:65]
	v_mfma_f32_16x16x32_bf16 v[50:53], v[134:137], v[174:177], v[50:53]
	v_mfma_f32_16x16x32_bf16 v[46:49], v[142:145], v[174:177], v[46:49]
	v_mfma_f32_16x16x32_bf16 v[34:37], v[134:137], v[204:207], v[34:37]
	v_mfma_f32_16x16x32_bf16 v[30:33], v[142:145], v[204:207], v[30:33]
	v_mfma_f32_16x16x32_bf16 v[18:21], v[134:137], v[212:215], v[18:21]
	v_mfma_f32_16x16x32_bf16 v[10:13], v[142:145], v[212:215], v[10:13]
	v_mfma_f32_16x16x32_bf16 v[66:69], v[138:141], v[170:173], v[66:69]
	v_mfma_f32_16x16x32_bf16 v[62:65], v[146:149], v[170:173], v[62:65]
	v_mfma_f32_16x16x32_bf16 v[50:53], v[138:141], v[178:181], v[50:53]
	v_mfma_f32_16x16x32_bf16 v[46:49], v[146:149], v[178:181], v[46:49]
	v_mfma_f32_16x16x32_bf16 v[34:37], v[138:141], v[208:211], v[34:37]
	v_mfma_f32_16x16x32_bf16 v[30:33], v[146:149], v[208:211], v[30:33]
	v_mfma_f32_16x16x32_bf16 v[18:21], v[138:141], v[216:219], v[18:21]
	v_mfma_f32_16x16x32_bf16 v[10:13], v[146:149], v[216:219], v[10:13]
	s_setprio 0
	s_setprio 1
	v_mfma_f32_16x16x32_bf16 v[58:61], v[150:153], v[166:169], v[58:61]
	v_mfma_f32_16x16x32_bf16 v[54:57], v[158:161], v[166:169], v[54:57]
	v_mfma_f32_16x16x32_bf16 v[42:45], v[150:153], v[174:177], v[42:45]
	v_mfma_f32_16x16x32_bf16 v[38:41], v[158:161], v[174:177], v[38:41]
	v_mfma_f32_16x16x32_bf16 v[26:29], v[150:153], v[204:207], v[26:29]
	v_mfma_f32_16x16x32_bf16 v[22:25], v[158:161], v[204:207], v[22:25]
	v_mfma_f32_16x16x32_bf16 v[6:9], v[150:153], v[212:215], v[6:9]
	v_mfma_f32_16x16x32_bf16 v[2:5], v[158:161], v[212:215], v[2:5]
	v_mfma_f32_16x16x32_bf16 v[58:61], v[154:157], v[170:173], v[58:61]
	v_mfma_f32_16x16x32_bf16 v[54:57], v[162:165], v[170:173], v[54:57]
	v_mfma_f32_16x16x32_bf16 v[42:45], v[154:157], v[178:181], v[42:45]
	v_mfma_f32_16x16x32_bf16 v[38:41], v[162:165], v[178:181], v[38:41]
	v_mfma_f32_16x16x32_bf16 v[26:29], v[154:157], v[208:211], v[26:29]
	v_mfma_f32_16x16x32_bf16 v[22:25], v[162:165], v[208:211], v[22:25]
	v_mfma_f32_16x16x32_bf16 v[6:9], v[154:157], v[216:219], v[6:9]
	v_mfma_f32_16x16x32_bf16 v[2:5], v[162:165], v[216:219], v[2:5]
	s_setprio 0
	s_barrier
	s_add_i32 s43, 0, 0x18000
	s_add_i32 s44, 0, 0x1c000
	s_add_u32 s22, s22, s4
	s_addc_u32 s23, s23, 0
	s_mov_b32 m0, s88
	s_nop 0
	global_load_lds_dwordx4 v14, s[22:23]
	s_mov_b32 m0, s89
	s_nop 0
	global_load_lds_dwordx4 v184, s[22:23]
	v_add_u32_e32 v0, s43, v234
	ds_read_b128 v[134:137], v0
	ds_read_b128 v[138:141], v0 offset:1024
	ds_read_b128 v[142:145], v0 offset:2048
	ds_read_b128 v[146:149], v0 offset:3072
	v_add_u32_e32 v0, s44, v234
	ds_read_b128 v[150:153], v0
	ds_read_b128 v[154:157], v0 offset:1024
	ds_read_b128 v[158:161], v0 offset:2048
	ds_read_b128 v[162:165], v0 offset:3072
	ds_read_b128 v[166:169], v242 offset:32768
	ds_read_b128 v[170:173], v242 offset:33792
	ds_read_b128 v[174:177], v242 offset:34816
	ds_read_b128 v[178:181], v242 offset:35840
	ds_read_b128 v[204:207], v242 offset:36864
	ds_read_b128 v[208:211], v242 offset:37888
	ds_read_b128 v[212:215], v242 offset:38912
	ds_read_b128 v[216:219], v242 offset:39936
	s_waitcnt vmcnt(8)
	s_waitcnt lgkmcnt(0)
	s_barrier
	s_setprio 1
	s_waitcnt lgkmcnt(0)
	v_mfma_f32_16x16x32_bf16 v[130:133], v[134:137], v[166:169], v[130:133]
	v_mfma_f32_16x16x32_bf16 v[126:129], v[142:145], v[166:169], v[126:129]
	v_mfma_f32_16x16x32_bf16 v[114:117], v[134:137], v[174:177], v[114:117]
	v_mfma_f32_16x16x32_bf16 v[110:113], v[142:145], v[174:177], v[110:113]
	v_mfma_f32_16x16x32_bf16 v[98:101], v[134:137], v[204:207], v[98:101]
	v_mfma_f32_16x16x32_bf16 v[94:97], v[142:145], v[204:207], v[94:97]
	v_mfma_f32_16x16x32_bf16 v[82:85], v[134:137], v[212:215], v[82:85]
	v_mfma_f32_16x16x32_bf16 v[78:81], v[142:145], v[212:215], v[78:81]
	v_mfma_f32_16x16x32_bf16 v[130:133], v[138:141], v[170:173], v[130:133]
	v_mfma_f32_16x16x32_bf16 v[126:129], v[146:149], v[170:173], v[126:129]
	v_mfma_f32_16x16x32_bf16 v[114:117], v[138:141], v[178:181], v[114:117]
	v_mfma_f32_16x16x32_bf16 v[110:113], v[146:149], v[178:181], v[110:113]
	v_mfma_f32_16x16x32_bf16 v[98:101], v[138:141], v[208:211], v[98:101]
	v_mfma_f32_16x16x32_bf16 v[94:97], v[146:149], v[208:211], v[94:97]
	v_mfma_f32_16x16x32_bf16 v[82:85], v[138:141], v[216:219], v[82:85]
	v_mfma_f32_16x16x32_bf16 v[78:81], v[146:149], v[216:219], v[78:81]
	s_setprio 0
	s_setprio 1
	v_mfma_f32_16x16x32_bf16 v[122:125], v[150:153], v[166:169], v[122:125]
	v_mfma_f32_16x16x32_bf16 v[118:121], v[158:161], v[166:169], v[118:121]
	v_mfma_f32_16x16x32_bf16 v[106:109], v[150:153], v[174:177], v[106:109]
	v_mfma_f32_16x16x32_bf16 v[102:105], v[158:161], v[174:177], v[102:105]
	v_mfma_f32_16x16x32_bf16 v[90:93], v[150:153], v[204:207], v[90:93]
	v_mfma_f32_16x16x32_bf16 v[86:89], v[158:161], v[204:207], v[86:89]
	v_mfma_f32_16x16x32_bf16 v[74:77], v[150:153], v[212:215], v[74:77]
	v_mfma_f32_16x16x32_bf16 v[70:73], v[158:161], v[212:215], v[70:73]
	v_mfma_f32_16x16x32_bf16 v[122:125], v[154:157], v[170:173], v[122:125]
	v_mfma_f32_16x16x32_bf16 v[118:121], v[162:165], v[170:173], v[118:121]
	v_mfma_f32_16x16x32_bf16 v[106:109], v[154:157], v[178:181], v[106:109]
	v_mfma_f32_16x16x32_bf16 v[102:105], v[162:165], v[178:181], v[102:105]
	v_mfma_f32_16x16x32_bf16 v[90:93], v[154:157], v[208:211], v[90:93]
	v_mfma_f32_16x16x32_bf16 v[86:89], v[162:165], v[208:211], v[86:89]
	v_mfma_f32_16x16x32_bf16 v[74:77], v[154:157], v[216:219], v[74:77]
	v_mfma_f32_16x16x32_bf16 v[70:73], v[162:165], v[216:219], v[70:73]
	s_setprio 0
	s_barrier
; #define PG8_STAGE(bufoff, gbase, voff) do { _Pragma("unroll") for (int _i = 0; _i < 2; ++_i) \
;         __builtin_amdgcn_global_load_lds((const unsigned*)((const char*)(gbase) + (voff)[_i]), (LAS unsigned*)(lds + (bufoff) + ldsw + _i * 8192), 16, 0, 0); } while (0)
; #define PG8_LDA(dst, b, h) do { _Pragma("unroll") for (int m = 0; m < 4; ++m) _Pragma("unroll") for (int k = 0; k < 2; ++k) dst[m][k] = *(const LAS bf16x8*)(lds + PG8_SA(b, h) + aoff + m * 2048 + k * 1024); } while (0)
; #define PG8_MMA(ai, bj, At, Bt) do { __builtin_amdgcn_s_setprio(1); _Pragma("unroll") for (int m = 0; m < 4; ++m) _Pragma("unroll") for (int n = 0; n < 2; ++n) _Pragma("unroll") for (int k = 0; k < 2; ++k) \
;         acc[ai][bj][m][n] = __builtin_amdgcn_mfma_f32_16x16x32_bf16(Bt[n][k], At[m][k], acc[ai][bj][m][n], 0, 0, 0); __builtin_amdgcn_s_setprio(0); } while (0)
; #define PG8_WAIT_V(n) asm volatile("s_waitcnt vmcnt(" #n ")" ::: "memory")
; #define PG8_WAIT_L(n) asm volatile("s_waitcnt lgkmcnt(" #n ")" ::: "memory")
; #define PG8_BAR __builtin_amdgcn_s_barrier()
; #define PG8_SCHED __builtin_amdgcn_sched_barrier(0)
; template <class EpiT>
; __device__ __forceinline__ void gemm_phase(LAS unsigned char* lds, const Gemm g, const StaticOrder& S, const EpiT& E, int wv) {
;     ...
;             PG8_WAIT_V(8); PG8_WAIT_L(0); PG8_BAR; PG8_MMA(0, 0, At, B0); PG8_MMA(0, 1, At, B1); PG8_BAR; PG8_SCHED;
;             PG8_LDA(At, 1, 1); PG8_STAGE(PG8_SB(1, 0), b3, voffB); PG8_STAGE(PG8_SB(1, 1), b3 + hB, voffB); PG8_STAGE(PG8_SA(1, 0), a3, voffA);
;             PG8_WAIT_V(8); PG8_WAIT_L(0); PG8_BAR; PG8_MMA(1, 0, At, B0); PG8_MMA(1, 1, At, B1); PG8_BAR; PG8_SCHED;
	s_add_i32 s22, s43, s13
	s_mov_b32 m0, s22
	s_nop 0
	global_load_lds_dwordx4 v182, s[36:37]
	s_add_i32 m0, s22, 0x2000
	s_add_i32 s22, s44, s13
	global_load_lds_dwordx4 v186, s[36:37]
	s_mov_b32 m0, s22
	s_nop 0
	global_load_lds_dwordx4 v182, s[38:39]
	s_add_i32 m0, s22, 0x2000
	s_nop 0
	global_load_lds_dwordx4 v186, s[38:39]
	s_mov_b32 m0, s72
	s_nop 0
	global_load_lds_dwordx4 v14, s[46:47]
	s_mov_b32 m0, s73
	s_nop 0
	global_load_lds_dwordx4 v184, s[46:47]
	ds_read_b128 v[166:169], v242 offset:49152
	ds_read_b128 v[170:173], v242 offset:50176
	ds_read_b128 v[174:177], v242 offset:51200
	ds_read_b128 v[178:181], v242 offset:52224
	ds_read_b128 v[204:207], v242 offset:53248
	ds_read_b128 v[208:211], v242 offset:54272
	ds_read_b128 v[212:215], v242 offset:55296
	ds_read_b128 v[216:219], v242 offset:56320
	s_waitcnt vmcnt(8)
	s_waitcnt lgkmcnt(0)
	s_barrier
	s_setprio 1
	s_waitcnt lgkmcnt(0)
	v_mfma_f32_16x16x32_bf16 v[66:69], v[134:137], v[166:169], v[66:69]
	v_mfma_f32_16x16x32_bf16 v[62:65], v[142:145], v[166:169], v[62:65]
	v_mfma_f32_16x16x32_bf16 v[50:53], v[134:137], v[174:177], v[50:53]
	v_mfma_f32_16x16x32_bf16 v[46:49], v[142:145], v[174:177], v[46:49]
	v_mfma_f32_16x16x32_bf16 v[34:37], v[134:137], v[204:207], v[34:37]
	v_mfma_f32_16x16x32_bf16 v[30:33], v[142:145], v[204:207], v[30:33]
	v_mfma_f32_16x16x32_bf16 v[18:21], v[134:137], v[212:215], v[18:21]
	v_mfma_f32_16x16x32_bf16 v[10:13], v[142:145], v[212:215], v[10:13]
	v_mfma_f32_16x16x32_bf16 v[66:69], v[138:141], v[170:173], v[66:69]
	v_mfma_f32_16x16x32_bf16 v[62:65], v[146:149], v[170:173], v[62:65]
	v_mfma_f32_16x16x32_bf16 v[50:53], v[138:141], v[178:181], v[50:53]
	v_mfma_f32_16x16x32_bf16 v[46:49], v[146:149], v[178:181], v[46:49]
	v_mfma_f32_16x16x32_bf16 v[34:37], v[138:141], v[208:211], v[34:37]
	v_mfma_f32_16x16x32_bf16 v[30:33], v[146:149], v[208:211], v[30:33]
	v_mfma_f32_16x16x32_bf16 v[18:21], v[138:141], v[216:219], v[18:21]
	v_mfma_f32_16x16x32_bf16 v[10:13], v[146:149], v[216:219], v[10:13]
	s_setprio 0
	s_setprio 1
	v_mfma_f32_16x16x32_bf16 v[58:61], v[150:153], v[166:169], v[58:61]
	v_mfma_f32_16x16x32_bf16 v[54:57], v[158:161], v[166:169], v[54:57]
	v_mfma_f32_16x16x32_bf16 v[42:45], v[150:153], v[174:177], v[42:45]
	v_mfma_f32_16x16x32_bf16 v[38:41], v[158:161], v[174:177], v[38:41]
	v_mfma_f32_16x16x32_bf16 v[26:29], v[150:153], v[204:207], v[26:29]
	v_mfma_f32_16x16x32_bf16 v[22:25], v[158:161], v[204:207], v[22:25]
	v_mfma_f32_16x16x32_bf16 v[6:9], v[150:153], v[212:215], v[6:9]
	v_mfma_f32_16x16x32_bf16 v[2:5], v[158:161], v[212:215], v[2:5]
	v_mfma_f32_16x16x32_bf16 v[58:61], v[154:157], v[170:173], v[58:61]
	v_mfma_f32_16x16x32_bf16 v[54:57], v[162:165], v[170:173], v[54:57]
	v_mfma_f32_16x16x32_bf16 v[42:45], v[154:157], v[178:181], v[42:45]
	v_mfma_f32_16x16x32_bf16 v[38:41], v[162:165], v[178:181], v[38:41]
	v_mfma_f32_16x16x32_bf16 v[26:29], v[154:157], v[208:211], v[26:29]
	v_mfma_f32_16x16x32_bf16 v[22:25], v[162:165], v[208:211], v[22:25]
	v_mfma_f32_16x16x32_bf16 v[6:9], v[154:157], v[216:219], v[6:9]
	v_mfma_f32_16x16x32_bf16 v[2:5], v[162:165], v[216:219], v[2:5]
	s_setprio 0
	s_barrier
	s_add_u32 s0, s0, 0x100
	s_addc_u32 s1, s1, 0
	s_add_u32 s40, s40, 0x100
	s_addc_u32 s41, s41, 0
	s_cmp_ge_i32 s42, s81
	s_mov_b32 s22, s42
	s_cbranch_scc0 .LBB0_271
	s_and_b64 vcc, exec, s[16:17]
	s_cbranch_vccnz .LBB0_278
